# tail phase item loop: item index remapped (gMLP items take indices 344..607) so no workgroup gets 2 gMLP + 2 HGRN-a items; worst case 2 gMLP + 1 HGRN-a or 1 + 3
# speedup vs baseline: 1.0062x; 1.0062x over previous
; #define RETID() do { tid = tidx(); lane = tid & 63; wave = tid >> 6; gw = bid * 8 + wave; } while (0)
; __global__ void __launch_bounds__(512, 2) mega(Params p) {
;     ...
;           else { split_wait(sw_, bst[1], tid);
;               const float* LB0 = LB + (size_t)l * 512; const float* LB1 = LB + (size_t)(4 + l) * 512;
;               for (int it = bid - 32; it < 264 + 528; it += G - 32) { RETID();
.LBB0_336:
	s_or_b64 exec, exec, s[34:35]
	v_readlane_b32 s0, v252, 50
	v_readlane_b32 s1, v252, 51
	s_andn2_b64 vcc, exec, s[0:1]
	s_waitcnt lgkmcnt(0)
	s_barrier
	s_cbranch_vccnz .LBB0_381
	s_lshl_b64 s[0:1], s[56:57], 11
	v_readlane_b32 s16, v251, 38
	v_readlane_b32 s17, v251, 39
	s_add_u32 s6, s16, s0
	s_addc_u32 s7, s17, s1
	s_lshl_b32 s84, s56, 9
	s_lshl_b64 s[12:13], s[84:85], 2
	s_add_u32 s11, s16, s12
	s_addc_u32 s12, s17, s13
	s_add_u32 s11, s11, 0x2000
	v_readlane_b32 s40, v251, 18
	s_addc_u32 s12, s12, 0
	v_readlane_b32 s48, v251, 26
	v_readlane_b32 s41, v251, 19
	v_readlane_b32 s49, v251, 27
	s_add_u32 s48, s40, s0
	v_readlane_b32 s42, v251, 20
	v_readlane_b32 s50, v251, 28
	s_addc_u32 s49, s41, s1
	v_readlane_b32 s43, v251, 21
	v_readlane_b32 s51, v251, 29
	s_add_u32 s50, s42, s0
	v_readlane_b32 s44, v251, 22
	s_addc_u32 s51, s43, s1
	s_lshl_b64 s[16:17], s[56:57], 18
	v_readlane_b32 s45, v251, 23
	s_add_u32 s13, s44, s16
	v_readlane_b32 s46, v251, 24
	v_readlane_b32 s52, v251, 30
	s_addc_u32 s16, s45, s17
	v_readlane_b32 s47, v251, 25
	v_readlane_b32 s53, v251, 31
	s_add_u32 s52, s46, s0
	v_readlane_b32 s65, v254, 52
	s_addc_u32 s53, s47, s1
	s_movk_i32 s47, 0x1000
	v_readlane_b32 s17, v252, 49
	v_readlane_b32 s54, v251, 32
	v_readlane_b32 s55, v251, 33
	s_mov_b32 s101, s17
	s_branch .LBB0_340

; #define RETID() do { tid = tidx(); lane = tid & 63; wave = tid >> 6; gw = bid * 8 + wave; } while (0)
; __global__ void __launch_bounds__(512, 2) mega(Params p) {
;     ...
;               for (int it = bid - 32; it < 264 + 528; it += G - 32) { RETID();
;                   if (it < 264) gmlp_item(P, p.in[8] + (size_t)l * 512, p.in[9] + (size_t)l * 512, p.in[10] + (size_t)l * 4 * 16384, p.in[11] + (size_t)l * 512, Y, it >> 2, it & 3, L, tid);
;                   else { const int r = it - 264; hgrn_a_item(P, LB0, LB1, ST, DT, r >> 2, r & 3, L, tid); } } } }
.LBB0_339:
	v_readlane_b32 s0, v252, 52
	s_add_i32 s101, s0, s101
	s_cmpk_lt_i32 s101, 0x318
	s_cbranch_scc0 .LBB0_381
.LBB0_340:
	s_mov_b32 s17, s101
	s_cmpk_lt_i32 s101, 0x158
	s_cbranch_scc0 .Litem_map1
	s_add_i32 s17, s101, 0x108
	s_branch .Litem_mapped
.Litem_map1:
	s_cmpk_lt_i32 s101, 0x260
	s_cbranch_scc0 .Litem_mapped
	s_add_i32 s17, s101, 0xfffffea8
